# attention: cross-half row max via v_permlane32_swap instead of ds_bpermute round trip
# baseline (speedup 1.0000x reference)
.LBB0_845:
	s_nop 9
	v_max_f32_e32 v201, v83, v83
	v_max_f32_e32 v208, v82, v82
	v_max_f32_e32 v201, v208, v201
	v_max3_f32 v201, v201, v84, v85
	v_max3_f32 v201, v201, v86, v87
	v_max3_f32 v201, v201, v88, v89
	v_max3_f32 v201, v201, v90, v91
	v_max3_f32 v201, v201, v92, v93
	v_max3_f32 v201, v201, v94, v95
	v_max3_f32 v201, v201, v96, v97
	v_mov_b32_e32 v208, v201
	s_nop 1
	v_permlane32_swap_b32_e32 v208, v201
	v_max_f32_e32 v201, v201, v208
	v_add_f32_e32 v208, 0x41000000, v191
	v_cmp_gt_f32_e32 vcc, v201, v208
	s_cbranch_vccz .LBB0_847
	v_max_f32_e32 v201, v201, v201
	v_max_f32_e32 v208, v191, v191
	v_max_f32_e32 v201, v208, v201
	v_sub_f32_e32 v191, v191, v201
	v_exp_f32_e32 v222, v191
	v_mov_b32_e32 v191, v201
	v_mul_f32_e32 v220, v220, v222
	v_pk_mul_f32 v[64:65], v[64:65], v[222:223] op_sel_hi:[1,0]
	v_pk_mul_f32 v[62:63], v[62:63], v[222:223] op_sel_hi:[1,0]
	v_pk_mul_f32 v[60:61], v[60:61], v[222:223] op_sel_hi:[1,0]
	v_pk_mul_f32 v[58:59], v[58:59], v[222:223] op_sel_hi:[1,0]
	v_pk_mul_f32 v[56:57], v[56:57], v[222:223] op_sel_hi:[1,0]
	v_pk_mul_f32 v[54:55], v[54:55], v[222:223] op_sel_hi:[1,0]
	v_pk_mul_f32 v[52:53], v[52:53], v[222:223] op_sel_hi:[1,0]
	v_pk_mul_f32 v[50:51], v[50:51], v[222:223] op_sel_hi:[1,0]
	v_pk_mul_f32 v[48:49], v[48:49], v[222:223] op_sel_hi:[1,0]
	v_pk_mul_f32 v[46:47], v[46:47], v[222:223] op_sel_hi:[1,0]
	v_pk_mul_f32 v[44:45], v[44:45], v[222:223] op_sel_hi:[1,0]
	v_pk_mul_f32 v[42:43], v[42:43], v[222:223] op_sel_hi:[1,0]
	v_pk_mul_f32 v[40:41], v[40:41], v[222:223] op_sel_hi:[1,0]
	v_pk_mul_f32 v[38:39], v[38:39], v[222:223] op_sel_hi:[1,0]
	v_pk_mul_f32 v[36:37], v[36:37], v[222:223] op_sel_hi:[1,0]
	v_pk_mul_f32 v[34:35], v[34:35], v[222:223] op_sel_hi:[1,0]
.LBB0_847:
	v_sub_f32_e32 v82, v82, v191
	v_sub_f32_e32 v83, v83, v191
	v_sub_f32_e32 v84, v84, v191
	v_sub_f32_e32 v85, v85, v191
	v_sub_f32_e32 v86, v86, v191
	v_sub_f32_e32 v87, v87, v191
	v_sub_f32_e32 v88, v88, v191
	v_sub_f32_e32 v89, v89, v191
	v_exp_f32_e32 v82, v82
	v_exp_f32_e32 v83, v83
	v_exp_f32_e32 v84, v84
	v_exp_f32_e32 v85, v85
	v_exp_f32_e32 v86, v86
	v_exp_f32_e32 v87, v87
	v_exp_f32_e32 v88, v88
	v_exp_f32_e32 v89, v89
	v_cvt_pk_bf16_f32 v222, v82, v83
	v_cvt_pk_bf16_f32 v223, v84, v85
	v_cvt_pk_bf16_f32 v224, v86, v87
	v_cvt_pk_bf16_f32 v225, v88, v89
	v_max_f32_e32 v201, v67, v67
	v_max_f32_e32 v208, v66, v66
	v_mfma_f32_32x32x16_bf16 v[50:65], v[158:161], v[222:225], v[50:65]
	v_max_f32_e32 v201, v208, v201
	v_max3_f32 v201, v201, v68, v69
	v_sub_f32_e32 v90, v90, v191
	v_sub_f32_e32 v91, v91, v191
	v_sub_f32_e32 v92, v92, v191
	v_sub_f32_e32 v93, v93, v191
	v_sub_f32_e32 v94, v94, v191
	v_mfma_f32_32x32x16_bf16 v[34:49], v[138:141], v[222:225], v[34:49]
	v_sub_f32_e32 v95, v95, v191
	v_sub_f32_e32 v96, v96, v191
	v_sub_f32_e32 v97, v97, v191
	v_max3_f32 v201, v201, v70, v71
	v_exp_f32_e32 v90, v90
	v_exp_f32_e32 v91, v91
	v_exp_f32_e32 v92, v92
	v_exp_f32_e32 v93, v93
	v_exp_f32_e32 v94, v94
	v_exp_f32_e32 v95, v95
	v_exp_f32_e32 v96, v96
	v_exp_f32_e32 v97, v97
	v_max3_f32 v201, v201, v72, v73
	v_max3_f32 v201, v201, v74, v75
	v_max3_f32 v201, v201, v76, v77
	v_max3_f32 v201, v201, v78, v79
	v_cvt_pk_bf16_f32 v226, v90, v91
	v_cvt_pk_bf16_f32 v227, v92, v93
	v_cvt_pk_bf16_f32 v228, v94, v95
	v_cvt_pk_bf16_f32 v229, v96, v97
	v_max3_f32 v201, v201, v80, v81
	v_mov_b32_e32 v208, v201
	v_mfma_f32_32x32x16_bf16 v[50:65], v[154:157], v[226:229], v[50:65]
	s_nop 0
	v_permlane32_swap_b32_e32 v208, v201
	v_max_f32_e32 v201, v201, v208
	v_add_f32_e32 v208, 0x41000000, v221
	v_cmp_gt_f32_e32 vcc, v201, v208
	v_mfma_f32_32x32x16_bf16 v[34:49], v[130:133], v[226:229], v[34:49]
	s_cbranch_vccz .LBB0_849
	v_max_f32_e32 v201, v201, v201
	v_max_f32_e32 v208, v221, v221
	v_max_f32_e32 v201, v208, v201
	v_sub_f32_e32 v208, v221, v201
	v_exp_f32_e32 v222, v208
	v_mov_b32_e32 v221, v201
	v_mul_f32_e32 v193, v193, v222
	v_pk_mul_f32 v[32:33], v[32:33], v[222:223] op_sel_hi:[1,0]
	v_pk_mul_f32 v[30:31], v[30:31], v[222:223] op_sel_hi:[1,0]
	v_pk_mul_f32 v[28:29], v[28:29], v[222:223] op_sel_hi:[1,0]
	v_pk_mul_f32 v[26:27], v[26:27], v[222:223] op_sel_hi:[1,0]
	v_pk_mul_f32 v[24:25], v[24:25], v[222:223] op_sel_hi:[1,0]
	v_pk_mul_f32 v[22:23], v[22:23], v[222:223] op_sel_hi:[1,0]
	v_pk_mul_f32 v[20:21], v[20:21], v[222:223] op_sel_hi:[1,0]
	v_pk_mul_f32 v[18:19], v[18:19], v[222:223] op_sel_hi:[1,0]
	v_pk_mul_f32 v[16:17], v[16:17], v[222:223] op_sel_hi:[1,0]
	v_pk_mul_f32 v[14:15], v[14:15], v[222:223] op_sel_hi:[1,0]
	v_pk_mul_f32 v[12:13], v[12:13], v[222:223] op_sel_hi:[1,0]
	v_pk_mul_f32 v[10:11], v[10:11], v[222:223] op_sel_hi:[1,0]
	v_pk_mul_f32 v[8:9], v[8:9], v[222:223] op_sel_hi:[1,0]
	v_pk_mul_f32 v[6:7], v[6:7], v[222:223] op_sel_hi:[1,0]
	v_pk_mul_f32 v[4:5], v[4:5], v[222:223] op_sel_hi:[1,0]
	v_pk_mul_f32 v[2:3], v[2:3], v[222:223] op_sel_hi:[1,0]
